# code placement: the four GEMM K-loop heads pinned to 64-byte boundaries (.p2align 6); in-proj/out-proj heads were at 20/28 mod 64
# speedup vs baseline: 1.0011x; 1.0011x over previous
;     __device__ __forceinline__ bool next(int i, Unit& u) const { if (i) return false; u.pm = pm; u.pn = pn; return true; }
;     __device__ __forceinline__ bool next(int i, Unit& u) const { if (i >= 5) return false; int t = i + rot; t = t >= 5 ? t - 5 : t; u.pm = pm; u.pn = e + 8 * t; return true; }
; template <class Epi, class Sched, bool ALIGN_EPI, bool SP2>
; __device__ __forceinline__ void gemm_phase(LAS unsigned char* lds, const Gemm g, const Sched& S, const Epi& E, int tid_in) {
;     ...
;     for (;;) {
;         const bool has_next = S.next(ui + 1, nxt);
;         const unsigned nA = has_next ? (unsigned)nxt.pm * tstepA : cA, nB = has_next ? (unsigned)nxt.pn * tstepB : cB;
;     ...
; #pragma unroll
;         for (int a = 0; a < 2; ++a)
; #pragma unroll
;             for (int b = 0; b < 2; ++b)
; #pragma unroll
;                 for (int m = 0; m < 4; ++m)
; #pragma unroll
;                     for (int n = 0; n < 2; ++n) acc[a][b][m][n] = (f32x4){0.f, 0.f, 0.f, 0.f};
;         cur = nxt; cA = nA; cB = nB; ++ui;
.LBB0_51:
	s_lshl_b32 s71, s61, 21
	s_and_b64 s[4:5], s[36:37], exec
	s_cselect_b32 s4, s71, s30
	s_lshl_b32 s70, s60, 21
	v_mov_b32_e32 v2, v1
	v_mov_b32_e32 v3, v1
	s_and_b64 s[14:15], s[36:37], exec
	v_mov_b32_e32 v0, v1
	v_mov_b64_e32 v[6:7], v[2:3]
	s_waitcnt vmcnt(19)
	v_mov_b64_e32 v[10:11], v[2:3]
	s_waitcnt vmcnt(16)
	v_mov_b64_e32 v[22:23], v[2:3]
	s_waitcnt vmcnt(15)
	v_mov_b64_e32 v[26:27], v[2:3]
	s_waitcnt vmcnt(14)
	v_mov_b64_e32 v[38:39], v[2:3]
	v_mov_b64_e32 v[42:43], v[2:3]
	v_mov_b64_e32 v[54:55], v[2:3]
	v_mov_b64_e32 v[58:59], v[2:3]
	v_mov_b64_e32 v[14:15], v[2:3]
	v_mov_b64_e32 v[18:19], v[2:3]
	v_mov_b64_e32 v[30:31], v[2:3]
	v_mov_b64_e32 v[34:35], v[2:3]
	v_mov_b64_e32 v[46:47], v[2:3]
	v_mov_b64_e32 v[50:51], v[2:3]
	v_mov_b64_e32 v[62:63], v[2:3]
	v_mov_b64_e32 v[66:67], v[2:3]
	v_mov_b64_e32 v[70:71], v[2:3]
	v_mov_b64_e32 v[74:75], v[2:3]
	v_mov_b64_e32 v[86:87], v[2:3]
	v_mov_b64_e32 v[90:91], v[2:3]
	v_mov_b64_e32 v[102:103], v[2:3]
	v_mov_b64_e32 v[106:107], v[2:3]
	v_mov_b64_e32 v[122:123], v[2:3]
	v_mov_b64_e32 v[126:127], v[2:3]
	v_mov_b64_e32 v[78:79], v[2:3]
	v_mov_b64_e32 v[82:83], v[2:3]
	v_mov_b64_e32 v[94:95], v[2:3]
	v_mov_b64_e32 v[98:99], v[2:3]
	v_mov_b64_e32 v[110:111], v[2:3]
	v_mov_b64_e32 v[118:119], v[2:3]
	v_mov_b64_e32 v[134:135], v[2:3]
	v_mov_b64_e32 v[138:139], v[2:3]
	s_cselect_b32 s5, s70, s31
	s_addk_i32 s31, 0x100
	s_mov_b32 s65, -2
	s_mov_b32 s66, 0
	v_mov_b64_e32 v[4:5], v[0:1]
	v_mov_b64_e32 v[8:9], v[0:1]
	v_mov_b64_e32 v[20:21], v[0:1]
	v_mov_b64_e32 v[24:25], v[0:1]
	v_mov_b64_e32 v[36:37], v[0:1]
	v_mov_b64_e32 v[40:41], v[0:1]
	v_mov_b64_e32 v[52:53], v[0:1]
	v_mov_b64_e32 v[56:57], v[0:1]
	v_mov_b64_e32 v[12:13], v[0:1]
	v_mov_b64_e32 v[16:17], v[0:1]
	v_mov_b64_e32 v[28:29], v[0:1]
	v_mov_b64_e32 v[32:33], v[0:1]
	v_mov_b64_e32 v[44:45], v[0:1]
	v_mov_b64_e32 v[48:49], v[0:1]
	v_mov_b64_e32 v[60:61], v[0:1]
	v_mov_b64_e32 v[64:65], v[0:1]
	v_mov_b64_e32 v[68:69], v[0:1]
	v_mov_b64_e32 v[72:73], v[0:1]
	v_mov_b64_e32 v[84:85], v[0:1]
	v_mov_b64_e32 v[88:89], v[0:1]
	v_mov_b64_e32 v[100:101], v[0:1]
	v_mov_b64_e32 v[104:105], v[0:1]
	v_mov_b64_e32 v[120:121], v[0:1]
	v_mov_b64_e32 v[124:125], v[0:1]
	v_mov_b64_e32 v[76:77], v[0:1]
	v_mov_b64_e32 v[80:81], v[0:1]
	v_mov_b64_e32 v[92:93], v[0:1]
	v_mov_b64_e32 v[96:97], v[0:1]
	v_mov_b64_e32 v[108:109], v[0:1]
	v_mov_b64_e32 v[116:117], v[0:1]
	v_mov_b64_e32 v[132:133], v[0:1]
	v_mov_b64_e32 v[136:137], v[0:1]
	s_branch .LBB0_53
	.p2align	6

;     __device__ __forceinline__ bool next(int i, Unit& u) const { if (i) return false; u.pm = pm; u.pn = pn; return true; }
;     __device__ __forceinline__ bool next(int i, Unit& u) const { if (i >= 5) return false; int t = i + rot; t = t >= 5 ? t - 5 : t; u.pm = pm; u.pn = e + 8 * t; return true; }
; template <class Epi, class Sched, bool ALIGN_EPI, bool SP2>
; __device__ __forceinline__ void gemm_phase(LAS unsigned char* lds, const Gemm g, const Sched& S, const Epi& E, int tid_in) {
;     ...
;     for (;;) {
;         const bool has_next = S.next(ui + 1, nxt);
;         const unsigned nA = has_next ? (unsigned)nxt.pm * tstepA : cA, nB = has_next ? (unsigned)nxt.pn * tstepB : cB;
;     ...
; #pragma unroll
;         for (int a = 0; a < 2; ++a)
; #pragma unroll
;             for (int b = 0; b < 2; ++b)
; #pragma unroll
;                 for (int m = 0; m < 4; ++m)
; #pragma unroll
;                     for (int n = 0; n < 2; ++n) acc[a][b][m][n] = (f32x4){0.f, 0.f, 0.f, 0.f};
;         cur = nxt; cA = nA; cB = nB; ++ui;
.LBB0_97:
	s_lshl_b32 s78, s77, 19
	s_and_b64 s[2:3], s[36:37], exec
	s_cselect_b32 s2, s78, s19
	s_lshl_b32 s79, s76, 19
	s_and_b64 s[14:15], s[36:37], exec
	v_mov_b32_e32 v2, 0
	v_mov_b32_e32 v243, 0x3e4ccccd
	v_mov_b32_e32 v236, 0x358637bd
	s_cselect_b32 s3, s79, s17
	s_add_i32 s16, s19, 0x40080
	s_addk_i32 s17, 0x100
	s_mov_b32 s19, -2
	v_mov_b32_e32 v3, v2
	v_mov_b32_e32 v4, v2
	v_mov_b32_e32 v5, v2
	v_mov_b32_e32 v6, v2
	v_mov_b32_e32 v7, v2
	v_mov_b32_e32 v8, v2
	v_mov_b32_e32 v9, v2
	s_waitcnt vmcnt(17)
	v_mov_b32_e32 v18, v2
	v_mov_b32_e32 v19, v2
	v_mov_b32_e32 v20, v2
	v_mov_b32_e32 v21, v2
	s_waitcnt vmcnt(16)
	v_mov_b32_e32 v22, v2
	v_mov_b32_e32 v23, v2
	v_mov_b32_e32 v24, v2
	v_mov_b32_e32 v25, v2
	s_waitcnt vmcnt(15)
	v_mov_b32_e32 v34, v2
	v_mov_b32_e32 v35, v2
	v_mov_b32_e32 v36, v2
	v_mov_b32_e32 v37, v2
	s_waitcnt vmcnt(14)
	v_mov_b32_e32 v38, v2
	v_mov_b32_e32 v39, v2
	v_mov_b32_e32 v40, v2
	v_mov_b32_e32 v41, v2
	v_mov_b32_e32 v58, v2
	v_mov_b32_e32 v59, v2
	v_mov_b32_e32 v60, v2
	v_mov_b32_e32 v61, v2
	v_mov_b32_e32 v62, v2
	v_mov_b32_e32 v63, v2
	v_mov_b32_e32 v64, v2
	v_mov_b32_e32 v65, v2
	v_mov_b32_e32 v10, v2
	v_mov_b32_e32 v11, v2
	v_mov_b32_e32 v12, v2
	v_mov_b32_e32 v13, v2
	v_mov_b32_e32 v14, v2
	v_mov_b32_e32 v15, v2
	v_mov_b32_e32 v16, v2
	v_mov_b32_e32 v17, v2
	v_mov_b32_e32 v26, v2
	v_mov_b32_e32 v27, v2
	v_mov_b32_e32 v28, v2
	v_mov_b32_e32 v29, v2
	v_mov_b32_e32 v30, v2
	v_mov_b32_e32 v31, v2
	v_mov_b32_e32 v32, v2
	v_mov_b32_e32 v33, v2
	v_mov_b32_e32 v42, v2
	v_mov_b32_e32 v43, v2
	v_mov_b32_e32 v44, v2
	v_mov_b32_e32 v45, v2
	v_mov_b32_e32 v46, v2
	v_mov_b32_e32 v47, v2
	v_mov_b32_e32 v48, v2
	v_mov_b32_e32 v49, v2
	v_mov_b32_e32 v74, v2
	v_mov_b32_e32 v75, v2
	v_mov_b32_e32 v76, v2
	v_mov_b32_e32 v77, v2
	v_mov_b32_e32 v78, v2
	v_mov_b32_e32 v79, v2
	v_mov_b32_e32 v80, v2
	v_mov_b32_e32 v81, v2
	v_mov_b32_e32 v82, v2
	v_mov_b32_e32 v83, v2
	v_mov_b32_e32 v84, v2
	v_mov_b32_e32 v85, v2
	v_mov_b32_e32 v86, v2
	v_mov_b32_e32 v87, v2
	v_mov_b32_e32 v88, v2
	v_mov_b32_e32 v89, v2
	v_mov_b32_e32 v98, v2
	v_mov_b32_e32 v99, v2
	v_mov_b32_e32 v100, v2
	v_mov_b32_e32 v101, v2
	v_mov_b32_e32 v102, v2
	v_mov_b32_e32 v103, v2
	v_mov_b32_e32 v104, v2
	v_mov_b32_e32 v105, v2
	v_mov_b32_e32 v116, v2
	v_mov_b32_e32 v117, v2
	v_mov_b32_e32 v118, v2
	v_mov_b32_e32 v119, v2
	v_mov_b32_e32 v120, v2
	v_mov_b32_e32 v121, v2
	v_mov_b32_e32 v122, v2
	v_mov_b32_e32 v123, v2
	v_mov_b32_e32 v140, v2
	v_mov_b32_e32 v141, v2
	v_mov_b32_e32 v142, v2
	v_mov_b32_e32 v143, v2
	v_mov_b32_e32 v144, v2
	v_mov_b32_e32 v145, v2
	v_mov_b32_e32 v146, v2
	v_mov_b32_e32 v147, v2
	v_mov_b32_e32 v90, v2
	v_mov_b32_e32 v91, v2
	v_mov_b32_e32 v92, v2
	v_mov_b32_e32 v93, v2
	v_mov_b32_e32 v94, v2
	v_mov_b32_e32 v95, v2
	v_mov_b32_e32 v96, v2
	v_mov_b32_e32 v97, v2
	v_mov_b32_e32 v106, v2
	v_mov_b32_e32 v107, v2
	v_mov_b32_e32 v108, v2
	v_mov_b32_e32 v109, v2
	v_mov_b32_e32 v110, v2
	v_mov_b32_e32 v111, v2
	v_mov_b32_e32 v112, v2
	v_mov_b32_e32 v113, v2
	v_mov_b32_e32 v124, v2
	v_mov_b32_e32 v125, v2
	v_mov_b32_e32 v126, v2
	v_mov_b32_e32 v127, v2
	v_mov_b32_e32 v128, v2
	v_mov_b32_e32 v129, v2
	v_mov_b32_e32 v130, v2
	v_mov_b32_e32 v131, v2
	v_mov_b32_e32 v172, v2
	v_mov_b32_e32 v173, v2
	v_mov_b32_e32 v174, v2
	v_mov_b32_e32 v175, v2
	v_mov_b32_e32 v176, v2
	v_mov_b32_e32 v177, v2
	v_mov_b32_e32 v178, v2
	v_mov_b32_e32 v179, v2
	.p2align	6

; template <class Epi, class Sched, bool ALIGN_EPI, bool SP2>
; __device__ __forceinline__ void gemm_phase(LAS unsigned char* lds, const Gemm g, const Sched& S, const Epi& E, int tid_in) {
;     ...
; #pragma unroll
;         for (int a = 0; a < 2; ++a)
; #pragma unroll
;             for (int b = 0; b < 2; ++b)
; #pragma unroll
;                 for (int m = 0; m < 4; ++m)
; #pragma unroll
;                     for (int n = 0; n < 2; ++n) acc[a][b][m][n] = (f32x4){0.f, 0.f, 0.f, 0.f};
;         cur = nxt; cA = nA; cB = nB; ++ui;
.Lprio_skip:
	s_mov_b32 s57, s9
	s_add_i32 s9, s9, 1
	s_add_i32 s2, s9, s31
	s_lshl_b32 s3, s2, 3
	s_sub_i32 s10, s3, 40
	s_cmp_gt_u32 s2, 4
	s_cselect_b32 s2, s10, s3
	s_add_i32 s2, s2, s30
	s_cmp_lt_u32 s57, 4
	s_mov_b32 s6, s66
	s_cselect_b32 s66, s2, s66
	s_mov_b32 s5, s71
	s_lshl_b32 s71, s66, 21
	s_cmp_lt_u32 s57, 4
	s_mov_b32 s7, s56
	s_cselect_b32 s56, s25, s56
	s_mov_b32 s4, s76
	s_cselect_b32 s2, s71, s5
	s_lshl_b32 s76, s56, 21
	s_cmp_lt_u32 s57, 4
	v_mov_b32_e32 v66, 0
	s_cselect_b32 s3, s76, s4
	s_add_i32 s4, s4, 0x100080
	s_addk_i32 s5, 0x100
	s_mov_b32 s10, -2
	v_mov_b32_e32 v67, v66
	v_mov_b32_e32 v68, v66
	v_mov_b32_e32 v69, v66
	v_mov_b32_e32 v70, v66
	v_mov_b32_e32 v71, v66
	v_mov_b32_e32 v72, v66
	v_mov_b32_e32 v73, v66
	v_mov_b32_e32 v82, v66
	v_mov_b32_e32 v83, v66
	v_mov_b32_e32 v84, v66
	v_mov_b32_e32 v85, v66
	v_mov_b32_e32 v86, v66
	v_mov_b32_e32 v87, v66
	v_mov_b32_e32 v88, v66
	v_mov_b32_e32 v89, v66
	v_mov_b32_e32 v98, v66
	v_mov_b32_e32 v99, v66
	v_mov_b32_e32 v100, v66
	v_mov_b32_e32 v101, v66
	v_mov_b32_e32 v102, v66
	v_mov_b32_e32 v103, v66
	v_mov_b32_e32 v104, v66
	v_mov_b32_e32 v105, v66
	v_mov_b32_e32 v116, v66
	v_mov_b32_e32 v117, v66
	v_mov_b32_e32 v118, v66
	v_mov_b32_e32 v119, v66
	v_mov_b32_e32 v120, v66
	v_mov_b32_e32 v121, v66
	v_mov_b32_e32 v122, v66
	v_mov_b32_e32 v123, v66
	v_mov_b32_e32 v74, v66
	v_mov_b32_e32 v75, v66
	v_mov_b32_e32 v76, v66
	v_mov_b32_e32 v77, v66
	v_mov_b32_e32 v78, v66
	v_mov_b32_e32 v79, v66
	v_mov_b32_e32 v80, v66
	v_mov_b32_e32 v81, v66
	v_mov_b32_e32 v90, v66
	v_mov_b32_e32 v91, v66
	v_mov_b32_e32 v92, v66
	v_mov_b32_e32 v93, v66
	v_mov_b32_e32 v94, v66
	v_mov_b32_e32 v95, v66
	v_mov_b32_e32 v96, v66
	v_mov_b32_e32 v97, v66
	v_mov_b32_e32 v106, v66
	v_mov_b32_e32 v107, v66
	v_mov_b32_e32 v108, v66
	v_mov_b32_e32 v109, v66
	v_mov_b32_e32 v110, v66
	v_mov_b32_e32 v111, v66
	v_mov_b32_e32 v112, v66
	v_mov_b32_e32 v113, v66
	v_mov_b32_e32 v124, v66
	v_mov_b32_e32 v125, v66
	v_mov_b32_e32 v126, v66
	v_mov_b32_e32 v127, v66
	v_mov_b32_e32 v128, v66
	v_mov_b32_e32 v129, v66
	v_mov_b32_e32 v130, v66
	v_mov_b32_e32 v131, v66
	v_mov_b32_e32 v50, v66
	v_mov_b32_e32 v51, v66
	v_mov_b32_e32 v52, v66
	v_mov_b32_e32 v53, v66
	v_mov_b32_e32 v54, v66
	v_mov_b32_e32 v55, v66
	v_mov_b32_e32 v56, v66
	v_mov_b32_e32 v57, v66
	v_mov_b32_e32 v132, v66
	v_mov_b32_e32 v133, v66
	v_mov_b32_e32 v134, v66
	v_mov_b32_e32 v135, v66
	v_mov_b32_e32 v136, v66
	v_mov_b32_e32 v137, v66
	v_mov_b32_e32 v138, v66
	v_mov_b32_e32 v139, v66
	v_mov_b32_e32 v148, v66
	v_mov_b32_e32 v149, v66
	v_mov_b32_e32 v150, v66
	v_mov_b32_e32 v151, v66
	v_mov_b32_e32 v152, v66
	v_mov_b32_e32 v153, v66
	v_mov_b32_e32 v154, v66
	v_mov_b32_e32 v155, v66
	s_waitcnt vmcnt(15)
	v_mov_b32_e32 v34, v66
	v_mov_b32_e32 v35, v66
	v_mov_b32_e32 v36, v66
	v_mov_b32_e32 v37, v66
	s_waitcnt vmcnt(14)
	v_mov_b32_e32 v38, v66
	v_mov_b32_e32 v39, v66
	v_mov_b32_e32 v40, v66
	v_mov_b32_e32 v41, v66
	v_mov_b32_e32 v58, v66
	v_mov_b32_e32 v59, v66
	v_mov_b32_e32 v60, v66
	v_mov_b32_e32 v61, v66
	v_mov_b32_e32 v62, v66
	v_mov_b32_e32 v63, v66
	v_mov_b32_e32 v64, v66
	v_mov_b32_e32 v65, v66
	v_mov_b32_e32 v140, v66
	v_mov_b32_e32 v141, v66
	v_mov_b32_e32 v142, v66
	v_mov_b32_e32 v143, v66
	v_mov_b32_e32 v144, v66
	v_mov_b32_e32 v145, v66
	v_mov_b32_e32 v146, v66
	v_mov_b32_e32 v147, v66
	v_mov_b32_e32 v156, v66
	v_mov_b32_e32 v157, v66
	v_mov_b32_e32 v158, v66
	v_mov_b32_e32 v159, v66
	v_mov_b32_e32 v160, v66
	v_mov_b32_e32 v161, v66
	v_mov_b32_e32 v162, v66
	v_mov_b32_e32 v163, v66
	v_mov_b32_e32 v42, v66
	v_mov_b32_e32 v43, v66
	v_mov_b32_e32 v44, v66
	v_mov_b32_e32 v45, v66
	v_mov_b32_e32 v46, v66
	v_mov_b32_e32 v47, v66
	v_mov_b32_e32 v48, v66
	v_mov_b32_e32 v49, v66
	.p2align	6

;     __device__ __forceinline__ bool next(int i, Unit& u) const { if (i) return false; u.pm = pm; u.pn = pn; return true; }
;     __device__ __forceinline__ bool next(int i, Unit& u) const { if (i >= 5) return false; int t = i + rot; t = t >= 5 ? t - 5 : t; u.pm = pm; u.pn = e + 8 * t; return true; }
; template <class Epi, class Sched, bool ALIGN_EPI, bool SP2>
; __device__ __forceinline__ void gemm_phase(LAS unsigned char* lds, const Gemm g, const Sched& S, const Epi& E, int tid_in) {
;     ...
;     for (;;) {
;         const bool has_next = S.next(ui + 1, nxt);
;         const unsigned nA = has_next ? (unsigned)nxt.pm * tstepA : cA, nB = has_next ? (unsigned)nxt.pn * tstepB : cB;
;     ...
; #pragma unroll
;         for (int a = 0; a < 2; ++a)
; #pragma unroll
;             for (int b = 0; b < 2; ++b)
; #pragma unroll
;                 for (int m = 0; m < 4; ++m)
; #pragma unroll
;                     for (int n = 0; n < 2; ++n) acc[a][b][m][n] = (f32x4){0.f, 0.f, 0.f, 0.f};
;         cur = nxt; cA = nA; cB = nB; ++ui;
.LBB0_337:
	s_lshl_b32 s53, s52, 21
	s_and_b64 s[4:5], s[36:37], exec
	s_cselect_b32 s4, s53, s57
	s_lshl_b32 s54, s50, 21
	s_and_b64 s[14:15], s[36:37], exec
	v_mov_b32_e32 v2, 0
	s_cselect_b32 s5, s54, s58
	s_add_i32 s57, s57, 0x100080
	s_addk_i32 s58, 0x100
	s_mov_b32 s59, -2
	v_mov_b32_e32 v3, v2
	v_mov_b32_e32 v4, v2
	v_mov_b32_e32 v5, v2
	v_mov_b32_e32 v6, v2
	v_mov_b32_e32 v7, v2
	v_mov_b32_e32 v8, v2
	v_mov_b32_e32 v9, v2
	v_mov_b32_e32 v14, v2
	v_mov_b32_e32 v15, v2
	v_mov_b32_e32 v16, v2
	v_mov_b32_e32 v17, v2
	v_mov_b32_e32 v22, v2
	v_mov_b32_e32 v23, v2
	v_mov_b32_e32 v24, v2
	v_mov_b32_e32 v25, v2
	v_mov_b32_e32 v30, v2
	v_mov_b32_e32 v31, v2
	v_mov_b32_e32 v32, v2
	v_mov_b32_e32 v33, v2
	v_mov_b32_e32 v38, v2
	v_mov_b32_e32 v39, v2
	v_mov_b32_e32 v40, v2
	v_mov_b32_e32 v41, v2
	v_mov_b32_e32 v46, v2
	v_mov_b32_e32 v47, v2
	v_mov_b32_e32 v48, v2
	v_mov_b32_e32 v49, v2
	v_mov_b32_e32 v54, v2
	v_mov_b32_e32 v55, v2
	v_mov_b32_e32 v56, v2
	v_mov_b32_e32 v57, v2
	v_mov_b32_e32 v10, v2
	v_mov_b32_e32 v11, v2
	v_mov_b32_e32 v12, v2
	v_mov_b32_e32 v13, v2
	v_mov_b32_e32 v18, v2
	v_mov_b32_e32 v19, v2
	v_mov_b32_e32 v20, v2
	v_mov_b32_e32 v21, v2
	v_mov_b32_e32 v26, v2
	v_mov_b32_e32 v27, v2
	v_mov_b32_e32 v28, v2
	v_mov_b32_e32 v29, v2
	v_mov_b32_e32 v34, v2
	v_mov_b32_e32 v35, v2
	v_mov_b32_e32 v36, v2
	v_mov_b32_e32 v37, v2
	v_mov_b32_e32 v42, v2
	v_mov_b32_e32 v43, v2
	v_mov_b32_e32 v44, v2
	v_mov_b32_e32 v45, v2
	v_mov_b32_e32 v50, v2
	v_mov_b32_e32 v51, v2
	v_mov_b32_e32 v52, v2
	v_mov_b32_e32 v53, v2
	v_mov_b32_e32 v58, v2
	v_mov_b32_e32 v59, v2
	v_mov_b32_e32 v60, v2
	v_mov_b32_e32 v61, v2
	v_mov_b32_e32 v62, v2
	v_mov_b32_e32 v63, v2
	v_mov_b32_e32 v64, v2
	v_mov_b32_e32 v65, v2
	v_mov_b32_e32 v66, v2
	v_mov_b32_e32 v67, v2
	v_mov_b32_e32 v68, v2
	v_mov_b32_e32 v69, v2
	v_mov_b32_e32 v70, v2
	v_mov_b32_e32 v71, v2
	v_mov_b32_e32 v72, v2
	v_mov_b32_e32 v73, v2
	v_mov_b32_e32 v78, v2
	v_mov_b32_e32 v79, v2
	v_mov_b32_e32 v80, v2
	v_mov_b32_e32 v81, v2
	v_mov_b32_e32 v86, v2
	v_mov_b32_e32 v87, v2
	v_mov_b32_e32 v88, v2
	v_mov_b32_e32 v89, v2
	v_mov_b32_e32 v94, v2
	v_mov_b32_e32 v95, v2
	v_mov_b32_e32 v96, v2
	v_mov_b32_e32 v97, v2
	v_mov_b32_e32 v102, v2
	v_mov_b32_e32 v103, v2
	v_mov_b32_e32 v104, v2
	v_mov_b32_e32 v105, v2
	v_mov_b32_e32 v110, v2
	v_mov_b32_e32 v111, v2
	v_mov_b32_e32 v112, v2
	v_mov_b32_e32 v113, v2
	v_mov_b32_e32 v120, v2
	v_mov_b32_e32 v121, v2
	v_mov_b32_e32 v122, v2
	v_mov_b32_e32 v123, v2
	v_mov_b32_e32 v74, v2
	v_mov_b32_e32 v75, v2
	v_mov_b32_e32 v76, v2
	v_mov_b32_e32 v77, v2
	v_mov_b32_e32 v82, v2
	v_mov_b32_e32 v83, v2
	v_mov_b32_e32 v84, v2
	v_mov_b32_e32 v85, v2
	v_mov_b32_e32 v90, v2
	v_mov_b32_e32 v91, v2
	v_mov_b32_e32 v92, v2
	v_mov_b32_e32 v93, v2
	v_mov_b32_e32 v98, v2
	v_mov_b32_e32 v99, v2
	v_mov_b32_e32 v100, v2
	v_mov_b32_e32 v101, v2
	v_mov_b32_e32 v106, v2
	v_mov_b32_e32 v107, v2
	v_mov_b32_e32 v108, v2
	v_mov_b32_e32 v109, v2
	v_mov_b32_e32 v116, v2
	v_mov_b32_e32 v117, v2
	v_mov_b32_e32 v118, v2
	v_mov_b32_e32 v119, v2
	v_mov_b32_e32 v124, v2
	v_mov_b32_e32 v125, v2
	v_mov_b32_e32 v126, v2
	v_mov_b32_e32 v127, v2
	v_mov_b32_e32 v128, v2
	v_mov_b32_e32 v129, v2
	v_mov_b32_e32 v130, v2
	v_mov_b32_e32 v131, v2
	.p2align	6
